# hand-written fixed-reference tile body for mixer-B attention: batched LDS reads, V frags shared by both softmax maps, no accumulator copies
# speedup vs baseline: 1.0711x; 1.0711x over previous
; #define MFMA(a, b, c) __builtin_amdgcn_mfma_f32_32x32x16_bf16((a), (b), (c), 0, 0, 0)
; template <int NS>
; DI void attn_item(const Params& p, int layer, char* smem, VBC& vc, int b, int hq, int qblk) {
;     ...
;     for (int it = 0; it < ntiles; ++it) {
;         const int buf = it & 1;
;         if (it + 1 < ntiles) dma_tile(it + 1, buf ^ 1);
;         const u16* cK = sK + buf * 8192; const u16* cV = cK + 4096;
;         const bool is_lat = it < lat1 - lat0;
;         const int kpos0 = (lat0 + it) * 64;
;         auto qk = [&](const int m, f32x16 (&s)[2]) {
; #pragma unroll
;             for (int kt2 = 0; kt2 < 2; ++kt2)
; #pragma unroll
;                 for (int e = 0; e < 16; ++e) s[kt2][e] = 0.f;
;             __builtin_amdgcn_s_setprio(1);
; #pragma unroll
;             for (int ks = 0; ks < NKS; ++ks)
; #pragma unroll
;                 for (int kt2 = 0; kt2 < 2; ++kt2) s[kt2] = MFMA(ld8(cK + (kt2 * 32 + r) * 64 + (((m * DQK + ks * 16)) ^ hs16)), qf[m][ks], s[kt2]);
; #pragma unroll
;             for (int kt2 = 0; kt2 < 2; ++kt2) { uint4 qa4 = {qaug[m], 0u, 0u, 0u}; s[kt2] = MFMA(kones, __builtin_bit_cast(bf16x8, qa4), s[kt2]); }
;             __builtin_amdgcn_s_setprio(0);
;         };
;         auto softmax = [&](const int m, f32x16 (&s)[2], bf16x8 (&pf)[2][2]) {
;             const bool fixed = fast && it > 0;
;             if (NS == 1 && is_lat) {
.LBB0_945:
	s_cmp_eq_u32 s46, 0
	s_cbranch_scc1 .Lorig_945B
	s_and_b64 vcc, exec, s[14:15]
	s_cbranch_vccnz .Lfb_tileB

; DI int lane_id() { int l; asm volatile("v_mbcnt_lo_u32_b32 %0, -1, 0\n\tv_mbcnt_hi_u32_b32 %0, -1, %0" : "=v"(l)); return l; }
; #define VSYNC() vb_sync(vc)
; DI void vb_sync(VBC& vc) {
;     vc.gen += 4u;
;     __builtin_amdgcn_fence(__ATOMIC_RELEASE, "workgroup");
;     asm volatile("s_waitcnt lgkmcnt(0)" ::: "memory");
;     if (lane_id() == 0) __hip_atomic_fetch_add(vc.cnt, 1u, __ATOMIC_RELAXED, __HIP_MEMORY_SCOPE_WORKGROUP);
; template <int NS>
; DI void attn_item(const Params& p, int layer, char* smem, VBC& vc, int b, int hq, int qblk) {
;     ...
;         asm volatile("s_waitcnt vmcnt(0)" ::: "memory");
;         VSYNC();
.Lfb_tailB:
	s_waitcnt vmcnt(0)
	s_waitcnt vmcnt(0)
	s_waitcnt lgkmcnt(0)
	v_mbcnt_lo_u32_b32 v2, -1, 0
	v_mbcnt_hi_u32_b32 v2, -1, v2
	s_nop 0
	v_cmp_eq_u32_e32 vcc, 0, v2
	s_and_saveexec_b64 s[0:1], vcc
	s_cbranch_execz .LBB0_960
	s_mov_b64 s[16:17], exec
	v_mbcnt_lo_u32_b32 v2, s16, 0
	v_mbcnt_hi_u32_b32 v2, s17, v2
	v_cmp_eq_u32_e32 vcc, 0, v2
	s_and_b64 s[48:49], exec, vcc
	s_mov_b64 exec, s[48:49]
	s_bcnt1_i32_b64 s16, s[16:17]
	v_mov_b32_e32 v2, s35
	v_mov_b32_e32 v4, s16
	ds_add_u32 v2, v4

; #define MFMA(a, b, c) __builtin_amdgcn_mfma_f32_32x32x16_bf16((a), (b), (c), 0, 0, 0)
; DI int crow(int e, int h) { return (e & 3) + 8 * (e >> 2) + 4 * h; }
; template <int NS>
; DI void attn_item(const Params& p, int layer, char* smem, VBC& vc, int b, int hq, int qblk) {
;     ...
;         auto qk = [&](const int m, f32x16 (&s)[2]) {
; #pragma unroll
;             for (int kt2 = 0; kt2 < 2; ++kt2)
; #pragma unroll
;                 for (int e = 0; e < 16; ++e) s[kt2][e] = 0.f;
;             __builtin_amdgcn_s_setprio(1);
; #pragma unroll
;             for (int ks = 0; ks < NKS; ++ks)
; #pragma unroll
;                 for (int kt2 = 0; kt2 < 2; ++kt2) s[kt2] = MFMA(ld8(cK + (kt2 * 32 + r) * 64 + (((m * DQK + ks * 16)) ^ hs16)), qf[m][ks], s[kt2]);
; #pragma unroll
;             for (int kt2 = 0; kt2 < 2; ++kt2) { uint4 qa4 = {qaug[m], 0u, 0u, 0u}; s[kt2] = MFMA(kones, __builtin_bit_cast(bf16x8, qa4), s[kt2]); }
;             __builtin_amdgcn_s_setprio(0);
;         };
;         auto softmax = [&](const int m, f32x16 (&s)[2], bf16x8 (&pf)[2][2]) {
;             const bool fixed = fast && it > 0;
;             if (NS == 1 && is_lat) {
; #pragma unroll
;                 for (int kt2 = 0; kt2 < 2; ++kt2)
; #pragma unroll
;                     for (int e = 0; e < 16; ++e) {
;                         int d = kpos0 + kt2 * 32 + crow(e, h) - qpos;
;                         if (d > 128 || d < -128) s[kt2][e] = -1e30f;
;                     }
;             }
;             if (fixed) {
;                 float ls = 0.f;
; #pragma unroll
;                 for (int kt2 = 0; kt2 < 2; ++kt2)
; #pragma unroll
;                     for (int e = 0; e < 16; ++e) { const float pv = __builtin_amdgcn_exp2f(s[kt2][e]); s[kt2][e] = pv; ls += pv; }
;                 lrun[m] += ls;
.Lfb_tileB:
	s_setprio 1
	v_lshl_add_u32 v226, s17, 1, v248
	v_lshl_add_u32 v5, v201, 1, v226
	v_lshl_add_u32 v6, v245, 1, v226
	ds_read_b128 v[112:115], v5
	ds_read_b128 v[116:119], v5 offset:4096
	v_lshl_add_u32 v223, v246, 1, v226
	ds_read_b128 v[120:123], v6
	ds_read_b128 v[124:127], v6 offset:4096
	v_lshl_add_u32 v225, v247, 1, v226
	ds_read_b128 v[128:131], v223
	ds_read_b128 v[132:135], v223 offset:4096
	ds_read_b128 v[136:139], v225
	ds_read_b128 v[140:143], v225 offset:4096
	v_mov_b32_e32 v2, 0
	v_mov_b32_e32 v3, 0
	v_mov_b32_e32 v12, s52
	v_mov_b32_e32 v13, 0
	v_mov_b32_e32 v14, 0
	v_mov_b32_e32 v15, 0
	v_mov_b32_e32 v8, v192
	v_mov_b32_e32 v9, 0
	v_mov_b32_e32 v10, 0
	v_mov_b32_e32 v11, 0
	v_mov_b32_e32 v226, v7
	s_waitcnt lgkmcnt(7)
	v_mfma_f32_32x32x16_bf16 v[96:111], v[112:115], v[176:179], 0
	s_waitcnt lgkmcnt(6)
	v_mfma_f32_32x32x16_bf16 v[80:95], v[116:119], v[176:179], 0
	s_waitcnt lgkmcnt(5)
	v_mfma_f32_32x32x16_bf16 v[96:111], v[120:123], v[180:183], v[96:111]
	s_waitcnt lgkmcnt(4)
	v_mfma_f32_32x32x16_bf16 v[80:95], v[124:127], v[180:183], v[80:95]
	ds_read_b128 v[112:115], v5 offset:8192
	ds_read_b128 v[116:119], v5 offset:12288
	v_mfma_f32_32x32x16_bf16 v[96:111], v[12:15], v[0:3], v[96:111]
	ds_read_b128 v[120:123], v6 offset:8192
	ds_read_b128 v[124:127], v6 offset:12288
	v_mfma_f32_32x32x16_bf16 v[80:95], v[12:15], v[0:3], v[80:95]
	s_waitcnt lgkmcnt(7)
	v_mfma_f32_32x32x16_bf16 v[144:159], v[128:131], v[184:187], 0
	s_waitcnt lgkmcnt(6)
	v_mfma_f32_32x32x16_bf16 v[160:175], v[132:135], v[184:187], 0
	s_waitcnt lgkmcnt(5)
	v_mfma_f32_32x32x16_bf16 v[144:159], v[136:139], v[188:191], v[144:159]
	s_waitcnt lgkmcnt(4)
	v_mfma_f32_32x32x16_bf16 v[160:175], v[140:143], v[188:191], v[160:175]
	ds_read_b128 v[128:131], v223 offset:8192
	ds_read_b128 v[132:135], v223 offset:12288
	v_exp_f32_e32 v96, v96
	v_exp_f32_e32 v97, v97
	v_exp_f32_e32 v98, v98
	v_exp_f32_e32 v99, v99
	v_mfma_f32_32x32x16_bf16 v[144:159], v[12:15], v[8:11], v[144:159]
	ds_read_b128 v[136:139], v225 offset:8192
	ds_read_b128 v[140:143], v225 offset:12288
	v_add_f32_e32 v2, v96, v98
	v_add_f32_e32 v3, v97, v99
	v_exp_f32_e32 v100, v100
	v_exp_f32_e32 v101, v101
	v_add_f32_e32 v2, v2, v100
	v_add_f32_e32 v3, v3, v101
	v_mfma_f32_32x32x16_bf16 v[160:175], v[12:15], v[8:11], v[160:175]
	v_exp_f32_e32 v102, v102
	v_exp_f32_e32 v103, v103
	v_add_f32_e32 v2, v2, v102
	v_add_f32_e32 v3, v3, v103
	v_exp_f32_e32 v104, v104
	v_exp_f32_e32 v105, v105
	v_add_f32_e32 v2, v2, v104
	v_add_f32_e32 v3, v3, v105
	v_exp_f32_e32 v106, v106
	v_exp_f32_e32 v107, v107
	v_add_f32_e32 v2, v2, v106
	v_add_f32_e32 v3, v3, v107
	v_exp_f32_e32 v108, v108
	v_exp_f32_e32 v109, v109
	v_add_f32_e32 v2, v2, v108
	v_add_f32_e32 v3, v3, v109
	v_exp_f32_e32 v110, v110
	v_exp_f32_e32 v111, v111
	v_add_f32_e32 v2, v2, v110
	v_add_f32_e32 v3, v3, v111
	v_exp_f32_e32 v80, v80
	v_exp_f32_e32 v81, v81
	v_add_f32_e32 v2, v2, v80
	v_add_f32_e32 v3, v3, v81
	v_exp_f32_e32 v82, v82
	v_exp_f32_e32 v83, v83
	v_add_f32_e32 v2, v2, v82
	v_add_f32_e32 v3, v3, v83
	v_exp_f32_e32 v84, v84
	v_exp_f32_e32 v85, v85
	v_add_f32_e32 v2, v2, v84
	v_add_f32_e32 v3, v3, v85
	v_exp_f32_e32 v86, v86
	v_exp_f32_e32 v87, v87
	v_add_f32_e32 v2, v2, v86
	v_add_f32_e32 v3, v3, v87
	v_exp_f32_e32 v88, v88
	v_exp_f32_e32 v89, v89
	v_add_f32_e32 v2, v2, v88
	v_add_f32_e32 v3, v3, v89
	v_exp_f32_e32 v90, v90
	v_exp_f32_e32 v91, v91
	v_add_f32_e32 v2, v2, v90
	v_add_f32_e32 v3, v3, v91
	v_exp_f32_e32 v92, v92
	v_exp_f32_e32 v93, v93
	v_add_f32_e32 v2, v2, v92
	v_add_f32_e32 v3, v3, v93
	v_exp_f32_e32 v94, v94
	v_exp_f32_e32 v95, v95
	v_add_f32_e32 v2, v2, v94
	v_add_f32_e32 v3, v3, v95
	s_setprio 0
	v_cvt_pk_bf16_f32 v96, v96, v97
	v_cvt_pk_bf16_f32 v97, v98, v99
	v_cvt_pk_bf16_f32 v98, v100, v101
	v_cvt_pk_bf16_f32 v99, v102, v103
	v_cvt_pk_bf16_f32 v100, v104, v105
	v_cvt_pk_bf16_f32 v101, v106, v107
	v_cvt_pk_bf16_f32 v102, v108, v109
	v_cvt_pk_bf16_f32 v103, v110, v111
	v_cvt_pk_bf16_f32 v80, v80, v81
	v_cvt_pk_bf16_f32 v81, v82, v83
	v_cvt_pk_bf16_f32 v82, v84, v85
	v_cvt_pk_bf16_f32 v83, v86, v87
	v_cvt_pk_bf16_f32 v84, v88, v89
	v_cvt_pk_bf16_f32 v85, v90, v91
	v_cvt_pk_bf16_f32 v86, v92, v93
	v_cvt_pk_bf16_f32 v87, v94, v95
	v_add_f32_e32 v2, v2, v3
	v_add_f32_e32 v223, v194, v2
	s_setprio 1
	s_waitcnt lgkmcnt(7)
; #define MFMA(a, b, c) __builtin_amdgcn_mfma_f32_32x32x16_bf16((a), (b), (c), 0, 0, 0)
; template <int NS>
; DI void attn_item(const Params& p, int layer, char* smem, VBC& vc, int b, int hq, int qblk) {
;     ...
;             if (fixed) {
;                 float ls = 0.f;
; #pragma unroll
;                 for (int kt2 = 0; kt2 < 2; ++kt2)
; #pragma unroll
;                     for (int e = 0; e < 16; ++e) { const float pv = __builtin_amdgcn_exp2f(s[kt2][e]); s[kt2][e] = pv; ls += pv; }
;                 lrun[m] += ls;
;     ...
;             for (int kt2 = 0; kt2 < 2; ++kt2) { pf[kt2][0] = pack8(s[kt2], 0); pf[kt2][1] = pack8(s[kt2], 1); }
;         };
;         auto pvm = [&](const int m, const bf16x8 (&pf)[2][2]) {
;             __builtin_amdgcn_s_setprio(1);
; #pragma unroll
;             for (int kk = 0; kk < 4; ++kk)
; #pragma unroll
;                 for (int dvt = 0; dvt < 2; ++dvt) O[m][dvt] = MFMA(ld8(cV + (dvt * 32 + r) * 64 + ((kk * 16) ^ hs16)), pf[kk >> 1][kk & 1], O[m][dvt]);
;             __builtin_amdgcn_s_setprio(0);
;         };
	v_mfma_f32_32x32x16_bf16 v[64:79], v[112:115], v[96:99], v[64:79]
	v_exp_f32_e32 v144, v144
	v_exp_f32_e32 v145, v145
	v_exp_f32_e32 v146, v146
	v_exp_f32_e32 v147, v147
	v_add_f32_e32 v193, v144, v146
	v_add_f32_e32 v195, v145, v147
	v_exp_f32_e32 v148, v148
	v_exp_f32_e32 v149, v149
	s_waitcnt lgkmcnt(6)
	v_mfma_f32_32x32x16_bf16 v[32:47], v[116:119], v[96:99], v[32:47]
	v_add_f32_e32 v193, v193, v148
	v_add_f32_e32 v195, v195, v149
	v_exp_f32_e32 v150, v150
	v_exp_f32_e32 v151, v151
	v_add_f32_e32 v193, v193, v150
	v_add_f32_e32 v195, v195, v151
	v_exp_f32_e32 v152, v152
	v_exp_f32_e32 v153, v153
	s_waitcnt lgkmcnt(5)
	v_mfma_f32_32x32x16_bf16 v[64:79], v[120:123], v[100:103], v[64:79]
	v_add_f32_e32 v193, v193, v152
	v_add_f32_e32 v195, v195, v153
	v_exp_f32_e32 v154, v154
	v_exp_f32_e32 v155, v155
	v_add_f32_e32 v193, v193, v154
	v_add_f32_e32 v195, v195, v155
	v_exp_f32_e32 v156, v156
	v_exp_f32_e32 v157, v157
	s_waitcnt lgkmcnt(4)
	v_mfma_f32_32x32x16_bf16 v[32:47], v[124:127], v[100:103], v[32:47]
	v_add_f32_e32 v193, v193, v156
	v_add_f32_e32 v195, v195, v157
	v_exp_f32_e32 v158, v158
	v_exp_f32_e32 v159, v159
	v_add_f32_e32 v193, v193, v158
	v_add_f32_e32 v195, v195, v159
	v_exp_f32_e32 v160, v160
	v_exp_f32_e32 v161, v161
	s_waitcnt lgkmcnt(3)
	v_mfma_f32_32x32x16_bf16 v[64:79], v[128:131], v[80:83], v[64:79]
	v_add_f32_e32 v193, v193, v160
	v_add_f32_e32 v195, v195, v161
	v_exp_f32_e32 v162, v162
	v_exp_f32_e32 v163, v163
	v_add_f32_e32 v193, v193, v162
	v_add_f32_e32 v195, v195, v163
	v_exp_f32_e32 v164, v164
	v_exp_f32_e32 v165, v165
	s_waitcnt lgkmcnt(2)
	v_mfma_f32_32x32x16_bf16 v[32:47], v[132:135], v[80:83], v[32:47]
	v_add_f32_e32 v193, v193, v164
	v_add_f32_e32 v195, v195, v165
	v_exp_f32_e32 v166, v166
	v_exp_f32_e32 v167, v167
	v_add_f32_e32 v193, v193, v166
	v_add_f32_e32 v195, v195, v167
	v_exp_f32_e32 v168, v168
	v_exp_f32_e32 v169, v169
	s_waitcnt lgkmcnt(1)
	v_mfma_f32_32x32x16_bf16 v[64:79], v[136:139], v[84:87], v[64:79]
	v_add_f32_e32 v193, v193, v168
	v_add_f32_e32 v195, v195, v169
	v_exp_f32_e32 v170, v170
	v_exp_f32_e32 v171, v171
	v_add_f32_e32 v193, v193, v170
	v_add_f32_e32 v195, v195, v171
	v_exp_f32_e32 v172, v172
	v_exp_f32_e32 v173, v173
	s_waitcnt lgkmcnt(0)
	v_mfma_f32_32x32x16_bf16 v[32:47], v[140:143], v[84:87], v[32:47]
	v_add_f32_e32 v193, v193, v172
	v_add_f32_e32 v195, v195, v173
	v_exp_f32_e32 v174, v174
	v_exp_f32_e32 v175, v175
	v_add_f32_e32 v193, v193, v174
	v_add_f32_e32 v195, v195, v175
	s_setprio 0
	v_cvt_pk_bf16_f32 v144, v144, v145
	v_cvt_pk_bf16_f32 v145, v146, v147
	v_cvt_pk_bf16_f32 v146, v148, v149
	v_cvt_pk_bf16_f32 v147, v150, v151
	v_cvt_pk_bf16_f32 v148, v152, v153
	v_cvt_pk_bf16_f32 v149, v154, v155
	v_cvt_pk_bf16_f32 v150, v156, v157
	v_cvt_pk_bf16_f32 v151, v158, v159
	v_cvt_pk_bf16_f32 v160, v160, v161
	v_cvt_pk_bf16_f32 v161, v162, v163
	v_cvt_pk_bf16_f32 v162, v164, v165
	v_cvt_pk_bf16_f32 v163, v166, v167
	v_cvt_pk_bf16_f32 v164, v168, v169
	v_cvt_pk_bf16_f32 v165, v170, v171
	v_cvt_pk_bf16_f32 v166, v172, v173
	v_cvt_pk_bf16_f32 v167, v174, v175
	v_add_f32_e32 v193, v193, v195
	v_add_f32_e32 v193, v4, v193
	v_mov_b32_e32 v195, v192
	v_mov_b32_e32 v3, v0
	v_mov_b32_e32 v0, v249
	s_setprio 1
	v_mfma_f32_32x32x16_bf16 v[48:63], v[112:115], v[144:147], v[48:63]
	v_mfma_f32_32x32x16_bf16 v[16:31], v[116:119], v[144:147], v[16:31]
	v_mfma_f32_32x32x16_bf16 v[48:63], v[120:123], v[148:151], v[48:63]
	v_mfma_f32_32x32x16_bf16 v[16:31], v[124:127], v[148:151], v[16:31]
	v_mfma_f32_32x32x16_bf16 v[48:63], v[128:131], v[160:163], v[48:63]
	v_mfma_f32_32x32x16_bf16 v[16:31], v[132:135], v[160:163], v[16:31]
	v_mfma_f32_32x32x16_bf16 v[48:63], v[136:139], v[164:167], v[48:63]
	v_mfma_f32_32x32x16_bf16 v[16:31], v[140:143], v[164:167], v[16:31]
	s_setprio 0
	s_branch .Lfb_tailB
